# DSA flash loop: double-buffered K/V LDS tiles, one workgroup barrier per key tile instead of two; tile t+1 written to the other buffer at the top of iteration t, global prefetch two tiles ahead; LDS 7
# baseline (speedup 1.0000x reference)
_Z4mega6Params:
	s_load_dwordx2 s[94:95], s[0:1], 0xf0
	s_mov_b64 s[58:59], s[0:1]
	s_add_u32 s26, s58, 0xf0
	s_addc_u32 s27, s59, 0
	v_mov_b32_e32 v2, 0
	s_waitcnt lgkmcnt(0)
	s_cmp_lt_u32 s2, s94
	s_cselect_b32 s0, 12, 18
	s_add_u32 s0, s26, s0
	s_addc_u32 s1, s27, 0
	global_load_ushort v1, v2, s[0:1]
	v_and_b32_e32 v208, 0x3ff, v0
	v_mov_b32_e32 v3, v208
	s_mov_b32 s92, s2
	s_waitcnt vmcnt(0)
	v_readfirstlane_b32 s0, v1
	s_nop 1
	v_writelane_b32 v254, s0, 0
	v_cmp_eq_u32_e32 vcc, 0, v3
	s_and_saveexec_b64 s[0:1], vcc
	v_mov_b32_e32 v3, v2
	v_mov_b32_e32 v4, v2
	v_mov_b32_e32 v5, v2
	v_mov_b32_e32 v1, 0x12100
	ds_write_b128 v1, v[2:5]
	s_or_b64 exec, exec, s[0:1]
	s_load_dword s0, s[58:59], 0xf8
	s_waitcnt lgkmcnt(0)
	s_barrier
	v_mov_b32_e32 v1, v208
	v_writelane_b32 v254, s0, 2
	s_mov_b64 s[0:1], s[58:59]
	s_load_dwordx2 s[0:1], s[0:1], 0xe0
	s_getreg_b32 s6, hwreg(HW_REG_XCC_ID, 0, 4)
	s_waitcnt lgkmcnt(0)
	s_add_u32 s2, s0, 0x271e8800
	s_addc_u32 s3, s1, 0
	v_writelane_b32 v254, s2, 4
	v_cmp_eq_u32_e32 vcc, 0, v1
	s_nop 0
	v_writelane_b32 v254, s3, 5
	s_and_saveexec_b64 s[2:3], vcc
	s_cbranch_execz .LBB0_5
	s_mov_b64 s[4:5], exec
	v_mbcnt_lo_u32_b32 v1, s4, 0
	v_mbcnt_hi_u32_b32 v1, s5, v1
	v_cmp_eq_u32_e32 vcc, 0, v1
	s_and_b64 s[8:9], exec, vcc
	s_mov_b64 exec, s[8:9]
	s_cbranch_execz .LBB0_5
	s_lshl_b32 s6, s6, 8
	s_bcnt1_i32_b64 s4, s[4:5]
	s_and_b32 s6, s6, 0xf00
	v_mov_b32_e32 v2, s4
	v_readlane_b32 s4, v254, 4
	v_mov_b32_e32 v1, s6
	v_readlane_b32 s5, v254, 5
	s_nop 4
	global_atomic_add v1, v2, s[4:5] offset:1024

.LBB0_340:
	s_or_b64 exec, exec, s[8:9]
	s_waitcnt vmcnt(0)
	v_mov_b32_e32 v0, v208
	s_waitcnt lgkmcnt(0)
	s_barrier
	s_nop 0
	v_cmp_eq_u32_e32 vcc, 0, v0
	s_and_saveexec_b64 s[2:3], vcc
	s_cbranch_execz .LBB0_392
	v_mov_b32_e32 v0, 0x12100
	s_getreg_b32 s4, hwreg(HW_REG_XCC_ID, 0, 4)
	s_waitcnt vmcnt(0) expcnt(0) lgkmcnt(0)
	ds_read_b32 v2, v0
	v_mov_b32_e32 v0, 0x12104
	ds_read_b32 v0, v0
	s_and_b32 s24, s4, 15
	s_waitcnt lgkmcnt(1)
	v_cmp_ne_u32_e32 vcc, 0, v2
	s_cbranch_vccnz .LBB0_356
	s_add_u32 s4, s0, 0x271e8a00
	s_addc_u32 s5, s1, 0
	s_add_u32 s6, s0, 0x271e8c00
	s_addc_u32 s7, s1, 0
	s_add_u32 s8, s0, 0x271e8d00
	s_addc_u32 s9, s1, 0
	s_add_u32 s10, s0, 0x271e8e00
	s_addc_u32 s11, s1, 0
	s_add_u32 s12, s0, 0x271e8f00
	s_addc_u32 s13, s1, 0
	s_add_u32 s14, s0, 0x271e9000
	s_addc_u32 s15, s1, 0
	s_add_u32 s16, s0, 0x271e9100
	s_addc_u32 s17, s1, 0
	s_add_u32 s18, s0, 0x271e9200
	s_addc_u32 s19, s1, 0
	s_add_u32 s20, s0, 0x271e9300
	s_addc_u32 s21, s1, 0
	s_add_u32 s22, s0, 0x271e9400
	s_addc_u32 s23, s1, 0
	s_add_u32 s26, s0, 0x271e9500
	s_addc_u32 s27, s1, 0
	s_add_u32 s28, s0, 0x271e9600
	s_addc_u32 s29, s1, 0
	s_add_u32 s30, s0, 0x271e9700
	s_addc_u32 s31, s1, 0
	s_add_u32 s36, s0, 0x271e9800
	s_addc_u32 s37, s1, 0
	s_add_u32 s38, s0, 0x271e9900
	s_addc_u32 s39, s1, 0
	s_add_u32 s40, s0, 0x271e9a00
	s_addc_u32 s41, s1, 0
	s_mul_i32 s25, s95, s35
	s_add_u32 s42, s0, 0x271e9b00
	s_mul_i32 s25, s25, s94
	s_addc_u32 s43, s1, 0
	s_mov_b32 s33, 1
	v_mov_b32_e32 v16, 0
	s_branch .LBB0_344

.LBB0_355:
	s_cmp_eq_u32 s24, 0
	s_cselect_b64 vcc, -1, 0
	s_cmp_eq_u32 s24, 1
	v_cndmask_b32_e32 v16, 0, v15, vcc
	s_cselect_b64 vcc, -1, 0
	s_cmp_eq_u32 s24, 2
	v_cndmask_b32_e32 v16, v16, v0, vcc
	s_cselect_b64 vcc, -1, 0
	s_cmp_eq_u32 s24, 3
	v_cndmask_b32_e32 v16, v16, v1, vcc
	s_cselect_b64 vcc, -1, 0
	s_cmp_eq_u32 s24, 4
	v_cndmask_b32_e32 v16, v16, v2, vcc
	s_cselect_b64 vcc, -1, 0
	s_cmp_eq_u32 s24, 5
	v_cndmask_b32_e32 v16, v16, v3, vcc
	s_cselect_b64 vcc, -1, 0
	s_cmp_eq_u32 s24, 6
	v_cndmask_b32_e32 v16, v16, v4, vcc
	s_cselect_b64 vcc, -1, 0
	s_cmp_eq_u32 s24, 7
	v_cndmask_b32_e32 v16, v16, v5, vcc
	s_cselect_b64 vcc, -1, 0
	s_cmp_eq_u32 s24, 8
	v_cndmask_b32_e32 v16, v16, v6, vcc
	s_cselect_b64 vcc, -1, 0
	s_cmp_eq_u32 s24, 9
	v_cndmask_b32_e32 v16, v16, v7, vcc
	s_cselect_b64 vcc, -1, 0
	s_cmp_eq_u32 s24, 10
	v_cndmask_b32_e32 v16, v16, v8, vcc
	s_cselect_b64 vcc, -1, 0
	s_cmp_eq_u32 s24, 11
	v_cndmask_b32_e32 v16, v16, v9, vcc
	s_cselect_b64 vcc, -1, 0
	s_cmp_eq_u32 s24, 12
	v_cndmask_b32_e32 v16, v16, v10, vcc
	s_cselect_b64 vcc, -1, 0
	s_cmp_eq_u32 s24, 13
	v_cndmask_b32_e32 v16, v16, v11, vcc
	s_cselect_b64 vcc, -1, 0
	s_cmp_eq_u32 s24, 14
	v_cndmask_b32_e32 v16, v16, v12, vcc
	s_cselect_b64 vcc, -1, 0
	s_cmp_eq_u32 s24, 15
	v_cndmask_b32_e32 v16, v16, v13, vcc
	s_cselect_b64 vcc, -1, 0
	v_cndmask_b32_e32 v16, v16, v14, vcc
	v_cmp_ne_u32_e32 vcc, 0, v15
	s_nop 1
	v_cndmask_b32_e64 v15, 0, 1, vcc
	v_cmp_ne_u32_e32 vcc, 0, v0
	s_nop 1
	v_addc_co_u32_e32 v0, vcc, 0, v15, vcc
	v_cmp_ne_u32_e32 vcc, 0, v1
	s_nop 1
	v_cndmask_b32_e64 v1, 0, 1, vcc
	v_cmp_ne_u32_e32 vcc, 0, v2
	v_max_u32_e32 v2, 1, v16
	s_nop 0
	v_addc_co_u32_e32 v0, vcc, v0, v1, vcc
	v_cmp_ne_u32_e32 vcc, 0, v3
	s_nop 1
	v_cndmask_b32_e64 v1, 0, 1, vcc
	v_cmp_ne_u32_e32 vcc, 0, v4
	s_nop 1
	v_addc_co_u32_e32 v0, vcc, v0, v1, vcc
	v_cmp_ne_u32_e32 vcc, 0, v5
	s_nop 1
	v_cndmask_b32_e64 v1, 0, 1, vcc
	v_cmp_ne_u32_e32 vcc, 0, v6
	s_nop 1
	v_addc_co_u32_e32 v0, vcc, v0, v1, vcc
	v_cmp_ne_u32_e32 vcc, 0, v7
	s_nop 1
	v_cndmask_b32_e64 v1, 0, 1, vcc
	v_cmp_ne_u32_e32 vcc, 0, v8
	s_nop 1
	v_addc_co_u32_e32 v0, vcc, v0, v1, vcc
	v_cmp_ne_u32_e32 vcc, 0, v9
	s_nop 1
	v_cndmask_b32_e64 v1, 0, 1, vcc
	v_cmp_ne_u32_e32 vcc, 0, v10
	s_nop 1
	v_addc_co_u32_e32 v0, vcc, v0, v1, vcc
	v_cmp_ne_u32_e32 vcc, 0, v11
	s_nop 1
	v_cndmask_b32_e64 v1, 0, 1, vcc
	v_cmp_ne_u32_e32 vcc, 0, v12
	s_nop 1
	v_addc_co_u32_e32 v0, vcc, v0, v1, vcc
	v_cmp_ne_u32_e32 vcc, 0, v13
	s_nop 1
	v_cndmask_b32_e64 v1, 0, 1, vcc
	v_cmp_ne_u32_e32 vcc, 0, v14
	s_nop 1
	v_addc_co_u32_e32 v0, vcc, v0, v1, vcc
	v_mov_b32_e32 v1, 0x12100
	v_max_u32_e32 v0, 1, v0
	ds_write_b32 v1, v2
	v_mov_b32_e32 v1, 0x12104
	ds_write_b32 v1, v0

.LBB0_399:
	s_or_b64 exec, exec, s[0:1]
	v_readlane_b32 s0, v255, 10
	s_waitcnt vmcnt(0)
	v_readlane_b32 s1, v255, 11
	v_mov_b32_e32 v1, v208
	s_xor_b64 s[0:1], s[0:1], -1
	s_barrier
	s_nop 0
	v_cmp_eq_u32_e32 vcc, 0, v1
	s_and_saveexec_b64 s[2:3], vcc
	s_cbranch_execz .LBB0_451
	v_mov_b32_e32 v1, 0x12100
	s_getreg_b32 s4, hwreg(HW_REG_XCC_ID, 0, 4)
	s_waitcnt vmcnt(0) expcnt(0) lgkmcnt(0)
	ds_read_b32 v3, v1
	v_mov_b32_e32 v1, 0x12104
	ds_read_b32 v2, v1
	s_and_b32 s10, s4, 15
	s_waitcnt lgkmcnt(1)
	v_cmp_ne_u32_e32 vcc, 0, v3
	s_cbranch_vccnz .LBB0_415
	s_mov_b32 s11, 1
	s_branch .LBB0_403

.LBB0_414:
	s_cmp_eq_u32 s10, 0
	s_cselect_b64 vcc, -1, 0
	s_cmp_eq_u32 s10, 1
	v_cndmask_b32_e32 v17, 0, v1, vcc
	s_cselect_b64 vcc, -1, 0
	s_cmp_eq_u32 s10, 2
	v_cndmask_b32_e32 v17, v17, v2, vcc
	s_cselect_b64 vcc, -1, 0
	s_cmp_eq_u32 s10, 3
	v_cndmask_b32_e32 v17, v17, v3, vcc
	s_cselect_b64 vcc, -1, 0
	s_cmp_eq_u32 s10, 4
	v_cndmask_b32_e32 v17, v17, v4, vcc
	s_cselect_b64 vcc, -1, 0
	s_cmp_eq_u32 s10, 5
	v_cndmask_b32_e32 v17, v17, v5, vcc
	s_cselect_b64 vcc, -1, 0
	s_cmp_eq_u32 s10, 6
	v_cndmask_b32_e32 v17, v17, v6, vcc
	s_cselect_b64 vcc, -1, 0
	s_cmp_eq_u32 s10, 7
	v_cndmask_b32_e32 v17, v17, v7, vcc
	s_cselect_b64 vcc, -1, 0
	s_cmp_eq_u32 s10, 8
	v_cndmask_b32_e32 v17, v17, v8, vcc
	s_cselect_b64 vcc, -1, 0
	s_cmp_eq_u32 s10, 9
	v_cndmask_b32_e32 v17, v17, v9, vcc
	s_cselect_b64 vcc, -1, 0
	s_cmp_eq_u32 s10, 10
	v_cndmask_b32_e32 v17, v17, v10, vcc
	s_cselect_b64 vcc, -1, 0
	s_cmp_eq_u32 s10, 11
	v_cndmask_b32_e32 v17, v17, v11, vcc
	s_cselect_b64 vcc, -1, 0
	s_cmp_eq_u32 s10, 12
	v_cndmask_b32_e32 v17, v17, v12, vcc
	s_cselect_b64 vcc, -1, 0
	s_cmp_eq_u32 s10, 13
	v_cndmask_b32_e32 v17, v17, v13, vcc
	s_cselect_b64 vcc, -1, 0
	s_cmp_eq_u32 s10, 14
	v_cndmask_b32_e32 v17, v17, v14, vcc
	s_cselect_b64 vcc, -1, 0
	s_cmp_eq_u32 s10, 15
	v_cndmask_b32_e32 v17, v17, v15, vcc
	s_cselect_b64 vcc, -1, 0
	v_cndmask_b32_e32 v17, v17, v16, vcc
	v_cmp_ne_u32_e32 vcc, 0, v1
	s_nop 1
	v_cndmask_b32_e64 v1, 0, 1, vcc
	v_cmp_ne_u32_e32 vcc, 0, v2
	s_nop 1
	v_addc_co_u32_e32 v1, vcc, 0, v1, vcc
	v_cmp_ne_u32_e32 vcc, 0, v3
	v_max_u32_e32 v3, 1, v17
	s_nop 0
	v_cndmask_b32_e64 v2, 0, 1, vcc
	v_cmp_ne_u32_e32 vcc, 0, v4
	s_nop 1
	v_addc_co_u32_e32 v1, vcc, v1, v2, vcc
	v_cmp_ne_u32_e32 vcc, 0, v5
	s_nop 1
	v_cndmask_b32_e64 v2, 0, 1, vcc
	v_cmp_ne_u32_e32 vcc, 0, v6
	s_nop 1
	v_addc_co_u32_e32 v1, vcc, v1, v2, vcc
	v_cmp_ne_u32_e32 vcc, 0, v7
	s_nop 1
	v_cndmask_b32_e64 v2, 0, 1, vcc
	v_cmp_ne_u32_e32 vcc, 0, v8
	s_nop 1
	v_addc_co_u32_e32 v1, vcc, v1, v2, vcc
	v_cmp_ne_u32_e32 vcc, 0, v9
	s_nop 1
	v_cndmask_b32_e64 v2, 0, 1, vcc
	v_cmp_ne_u32_e32 vcc, 0, v10
	s_nop 1
	v_addc_co_u32_e32 v1, vcc, v1, v2, vcc
	v_cmp_ne_u32_e32 vcc, 0, v11
	s_nop 1
	v_cndmask_b32_e64 v2, 0, 1, vcc
	v_cmp_ne_u32_e32 vcc, 0, v12
	s_nop 1
	v_addc_co_u32_e32 v1, vcc, v1, v2, vcc
	v_cmp_ne_u32_e32 vcc, 0, v13
	s_nop 1
	v_cndmask_b32_e64 v2, 0, 1, vcc
	v_cmp_ne_u32_e32 vcc, 0, v14
	s_nop 1
	v_addc_co_u32_e32 v1, vcc, v1, v2, vcc
	v_cmp_ne_u32_e32 vcc, 0, v15
	s_nop 1
	v_cndmask_b32_e64 v2, 0, 1, vcc
	v_cmp_ne_u32_e32 vcc, 0, v16
	s_nop 1
	v_addc_co_u32_e32 v1, vcc, v1, v2, vcc
	v_max_u32_e32 v2, 1, v1
	v_mov_b32_e32 v1, 0x12100
	ds_write_b32 v1, v3
	v_mov_b32_e32 v1, 0x12104
	ds_write_b32 v1, v2

.LBB0_545:
	s_waitcnt vmcnt(0)
	v_mov_b32_e32 v1, v208
	s_waitcnt lgkmcnt(0)
	s_barrier
	s_nop 0
	v_cmp_eq_u32_e32 vcc, 0, v1
	s_and_saveexec_b64 s[0:1], vcc
	v_readlane_b32 s58, v254, 9
	v_readlane_b32 s59, v254, 10
	s_cbranch_execz .LBB0_597
	v_mov_b32_e32 v1, 0x12100
	s_getreg_b32 s2, hwreg(HW_REG_XCC_ID, 0, 4)
	s_waitcnt vmcnt(0) expcnt(0) lgkmcnt(0)
	ds_read_b32 v3, v1
	v_mov_b32_e32 v1, 0x12104
	ds_read_b32 v2, v1
	s_and_b32 s8, s2, 15
	s_waitcnt lgkmcnt(1)
	v_cmp_ne_u32_e32 vcc, 0, v3
	s_cbranch_vccnz .LBB0_561
	s_mov_b32 s9, 1
	s_branch .LBB0_549

.LBB0_560:
	s_cmp_eq_u32 s8, 0
	s_cselect_b64 vcc, -1, 0
	s_cmp_eq_u32 s8, 1
	v_cndmask_b32_e32 v17, 0, v1, vcc
	s_cselect_b64 vcc, -1, 0
	s_cmp_eq_u32 s8, 2
	v_cndmask_b32_e32 v17, v17, v2, vcc
	s_cselect_b64 vcc, -1, 0
	s_cmp_eq_u32 s8, 3
	v_cndmask_b32_e32 v17, v17, v3, vcc
	s_cselect_b64 vcc, -1, 0
	s_cmp_eq_u32 s8, 4
	v_cndmask_b32_e32 v17, v17, v4, vcc
	s_cselect_b64 vcc, -1, 0
	s_cmp_eq_u32 s8, 5
	v_cndmask_b32_e32 v17, v17, v5, vcc
	s_cselect_b64 vcc, -1, 0
	s_cmp_eq_u32 s8, 6
	v_cndmask_b32_e32 v17, v17, v6, vcc
	s_cselect_b64 vcc, -1, 0
	s_cmp_eq_u32 s8, 7
	v_cndmask_b32_e32 v17, v17, v7, vcc
	s_cselect_b64 vcc, -1, 0
	s_cmp_eq_u32 s8, 8
	v_cndmask_b32_e32 v17, v17, v8, vcc
	s_cselect_b64 vcc, -1, 0
	s_cmp_eq_u32 s8, 9
	v_cndmask_b32_e32 v17, v17, v9, vcc
	s_cselect_b64 vcc, -1, 0
	s_cmp_eq_u32 s8, 10
	v_cndmask_b32_e32 v17, v17, v10, vcc
	s_cselect_b64 vcc, -1, 0
	s_cmp_eq_u32 s8, 11
	v_cndmask_b32_e32 v17, v17, v11, vcc
	s_cselect_b64 vcc, -1, 0
	s_cmp_eq_u32 s8, 12
	v_cndmask_b32_e32 v17, v17, v12, vcc
	s_cselect_b64 vcc, -1, 0
	s_cmp_eq_u32 s8, 13
	v_cndmask_b32_e32 v17, v17, v13, vcc
	s_cselect_b64 vcc, -1, 0
	s_cmp_eq_u32 s8, 14
	v_cndmask_b32_e32 v17, v17, v14, vcc
	s_cselect_b64 vcc, -1, 0
	s_cmp_eq_u32 s8, 15
	v_cndmask_b32_e32 v17, v17, v15, vcc
	s_cselect_b64 vcc, -1, 0
	v_cndmask_b32_e32 v17, v17, v16, vcc
	v_cmp_ne_u32_e32 vcc, 0, v1
	s_nop 1
	v_cndmask_b32_e64 v1, 0, 1, vcc
	v_cmp_ne_u32_e32 vcc, 0, v2
	s_nop 1
	v_addc_co_u32_e32 v1, vcc, 0, v1, vcc
	v_cmp_ne_u32_e32 vcc, 0, v3
	v_max_u32_e32 v3, 1, v17
	s_nop 0
	v_cndmask_b32_e64 v2, 0, 1, vcc
	v_cmp_ne_u32_e32 vcc, 0, v4
	s_nop 1
	v_addc_co_u32_e32 v1, vcc, v1, v2, vcc
	v_cmp_ne_u32_e32 vcc, 0, v5
	s_nop 1
	v_cndmask_b32_e64 v2, 0, 1, vcc
	v_cmp_ne_u32_e32 vcc, 0, v6
	s_nop 1
	v_addc_co_u32_e32 v1, vcc, v1, v2, vcc
	v_cmp_ne_u32_e32 vcc, 0, v7
	s_nop 1
	v_cndmask_b32_e64 v2, 0, 1, vcc
	v_cmp_ne_u32_e32 vcc, 0, v8
	s_nop 1
	v_addc_co_u32_e32 v1, vcc, v1, v2, vcc
	v_cmp_ne_u32_e32 vcc, 0, v9
	s_nop 1
	v_cndmask_b32_e64 v2, 0, 1, vcc
	v_cmp_ne_u32_e32 vcc, 0, v10
	s_nop 1
	v_addc_co_u32_e32 v1, vcc, v1, v2, vcc
	v_cmp_ne_u32_e32 vcc, 0, v11
	s_nop 1
	v_cndmask_b32_e64 v2, 0, 1, vcc
	v_cmp_ne_u32_e32 vcc, 0, v12
	s_nop 1
	v_addc_co_u32_e32 v1, vcc, v1, v2, vcc
	v_cmp_ne_u32_e32 vcc, 0, v13
	s_nop 1
	v_cndmask_b32_e64 v2, 0, 1, vcc
	v_cmp_ne_u32_e32 vcc, 0, v14
	s_nop 1
	v_addc_co_u32_e32 v1, vcc, v1, v2, vcc
	v_cmp_ne_u32_e32 vcc, 0, v15
	s_nop 1
	v_cndmask_b32_e64 v2, 0, 1, vcc
	v_cmp_ne_u32_e32 vcc, 0, v16
	s_nop 1
	v_addc_co_u32_e32 v1, vcc, v1, v2, vcc
	v_max_u32_e32 v2, 1, v1
	v_mov_b32_e32 v1, 0x12100
	ds_write_b32 v1, v3
	v_mov_b32_e32 v1, 0x12104
	ds_write_b32 v1, v2

.LBB0_618:
	s_waitcnt vmcnt(0)
	v_mov_b32_e32 v1, v208
	s_barrier
	s_nop 0
	v_cmp_eq_u32_e32 vcc, 0, v1
	s_and_saveexec_b64 s[0:1], vcc
	s_cbranch_execz .LBB0_670
	v_mov_b32_e32 v1, 0x12100
	s_getreg_b32 s2, hwreg(HW_REG_XCC_ID, 0, 4)
	s_waitcnt vmcnt(0) expcnt(0) lgkmcnt(0)
	ds_read_b32 v3, v1
	v_mov_b32_e32 v1, 0x12104
	ds_read_b32 v2, v1
	s_and_b32 s8, s2, 15
	s_waitcnt lgkmcnt(1)
	v_cmp_ne_u32_e32 vcc, 0, v3
	s_cbranch_vccnz .LBB0_634
	s_mov_b32 s9, 1
	s_branch .LBB0_622

.LBB0_697:
	s_waitcnt vmcnt(0)
	v_mov_b32_e32 v1, v208
	s_waitcnt lgkmcnt(0)
	s_barrier
	s_nop 0
	v_cmp_eq_u32_e32 vcc, 0, v1
	s_and_saveexec_b64 s[0:1], vcc
	s_cbranch_execz .LBB0_749
	v_mov_b32_e32 v1, 0x12100
	s_getreg_b32 s2, hwreg(HW_REG_XCC_ID, 0, 4)
	s_waitcnt vmcnt(0) expcnt(0) lgkmcnt(0)
	ds_read_b32 v3, v1
	v_mov_b32_e32 v1, 0x12104
	ds_read_b32 v2, v1
	s_and_b32 s8, s2, 15
	s_waitcnt lgkmcnt(1)
	v_cmp_ne_u32_e32 vcc, 0, v3
	s_cbranch_vccnz .LBB0_713
	s_mov_b32 s9, 1
	s_branch .LBB0_701

.LBB0_756:
	s_andn2_saveexec_b64 s[4:5], s[4:5]
	v_max_i32_e32 v1, 0, v2
	s_or_b64 exec, exec, s[4:5]
	v_lshl_or_b32 v2, v1, 4, s21
	v_ashrrev_i32_e32 v3, 31, v2
	v_lshl_add_u64 v[2:3], v[2:3], 2, s[0:1]
	global_load_dword v1, v[2:3], off
	v_mov_b32_e32 v2, v208
	s_waitcnt vmcnt(0)
	v_mul_f32_e32 v1, 0x3fb8aa3b, v1
	v_lshlrev_b32_e32 v2, 2, v2
	ds_write_b32 v2, v1 offset:34816
.LBB0_759:
	s_or_b64 exec, exec, s[2:3]
	s_lshl_b32 s2, s6, 2
	s_and_b32 s8, s2, 0xffffff80
	s_sub_i32 s9, 0x1f80, s8
	v_add_u32_e32 v1, s9, v199
	v_or_b32_e32 v2, v1, v197
	s_lshl_b32 s2, s6, 13
	s_and_b32 s84, s2, 0x3e000
	v_ashrrev_i32_e32 v3, 31, v2
	s_bfe_u32 s7, s6, 0x10004
	v_lshl_add_u64 v[4:5], v[2:3], 0, s[84:85]
	s_lshl_b32 s3, s21, 19
	v_lshlrev_b64 v[4:5], 8, v[4:5]
	s_lshl_b32 s2, s7, 23
	s_and_b32 s3, s3, 0x600000
	v_lshl_add_u64 v[4:5], v[176:177], 0, v[4:5]
	s_or_b32 s4, s2, s3
	v_mov_b32_e32 v22, v208
	s_waitcnt lgkmcnt(0)
	s_barrier
	global_load_dwordx4 v[112:115], v[4:5], off
	global_load_dwordx4 v[116:119], v[4:5], off offset:32
	global_load_dwordx4 v[120:123], v[4:5], off offset:64
	global_load_dwordx4 v[124:127], v[4:5], off offset:96
	global_load_dwordx4 v[128:131], v[4:5], off offset:128
	global_load_dwordx4 v[132:135], v[4:5], off offset:160
	global_load_dwordx4 v[136:139], v[4:5], off offset:192
	global_load_dwordx4 v[140:143], v[4:5], off offset:224
	s_add_u32 s2, s16, s4
	s_addc_u32 s3, s17, 0
	v_ashrrev_i32_e32 v182, 4, v22
	v_lshlrev_b32_e32 v10, 4, v22
	v_and_b32_e32 v16, 0xf0, v10
	v_mov_b32_e32 v17, v0
	v_ashrrev_i32_e32 v183, 31, v182
	v_lshl_add_u64 v[184:185], s[2:3], 0, v[16:17]
	v_lshlrev_b64 v[4:5], 8, v[182:183]
	v_lshl_add_u64 v[4:5], v[184:185], 0, v[4:5]
	v_add_co_u32_e32 v6, vcc, s61, v4
	s_add_u32 s4, s18, s4
	s_nop 0
	v_addc_co_u32_e32 v7, vcc, 0, v5, vcc
	s_movk_i32 s2, 0x3000
	v_and_b32_e32 v18, 0x70, v10
	v_ashrrev_i32_e32 v10, 3, v22
	s_addc_u32 s5, s19, 0
	v_add_co_u32_e32 v8, vcc, s2, v4
	v_mov_b32_e32 v19, v0
	v_ashrrev_i32_e32 v11, 31, v10
	v_addc_co_u32_e32 v9, vcc, 0, v5, vcc
	v_lshl_add_u64 v[186:187], s[4:5], 0, v[18:19]
	v_lshlrev_b64 v[188:189], 14, v[10:11]
	global_load_dwordx4 v[144:147], v[6:7], off
	v_lshl_add_u64 v[12:13], v[186:187], 0, v[188:189]
	global_load_dwordx4 v[148:151], v[8:9], off
	global_load_dwordx4 v[152:155], v[12:13], off
	v_add_u32_e32 v8, 0x100, v22
	v_ashrrev_i32_e32 v8, 3, v8
	v_ashrrev_i32_e32 v9, 31, v8
	v_lshlrev_b64 v[190:191], 14, v[8:9]
	v_add_u32_e32 v9, 0x200, v22
	v_ashrrev_i32_e32 v14, 3, v9
	v_ashrrev_i32_e32 v15, 31, v14
	s_lshl_b32 s6, s7, 13
	v_lshl_add_u64 v[12:13], v[186:187], 0, v[190:191]
	v_lshlrev_b64 v[192:193], 14, v[14:15]
	v_add_u32_e32 v9, 0x300, v22
	v_add_u32_e32 v180, s6, v2
	v_lshl_add_u64 v[20:21], v[186:187], 0, v[192:193]
	global_load_dwordx4 v[164:167], v[12:13], off
	global_load_dwordx4 v[168:171], v[20:21], off
	v_ashrrev_i32_e32 v12, 3, v9
	v_ashrrev_i32_e32 v181, 31, v180
	v_ashrrev_i32_e32 v13, 31, v12
	v_lshlrev_b64 v[2:3], 10, v[180:181]
	v_lshlrev_b64 v[194:195], 14, v[12:13]
	v_lshl_add_u64 v[2:3], s[10:11], 0, v[2:3]
	v_lshl_add_u64 v[20:21], v[186:187], 0, v[194:195]
	global_load_dwordx4 v[156:159], v[4:5], off
	global_load_dwordx2 v[202:203], v[2:3], off
	global_load_dwordx4 v[160:163], v[6:7], off offset:-4096
	global_load_dwordx4 v[172:175], v[20:21], off
	v_bfe_u32 v3, v22, 5, 1
	v_and_b32_e32 v2, 31, v22
	v_subrev_u32_e32 v183, 63, v1
	v_lshlrev_b32_e32 v17, 4, v3
	v_lshlrev_b32_e32 v1, 3, v3
	v_sub_u32_e32 v19, v17, v1
	v_or_b32_e32 v1, 32, v2
	v_mul_u32_u24_e32 v27, 0x88, v1
	v_mul_u32_u24_e32 v28, 0x110, v1
	v_add_u32_e32 v1, s6, v204
	ds_read_b32 v179, v0 offset:35328
	v_mul_u32_u24_e32 v20, 0x88, v2
	v_mul_u32_u24_e32 v26, 0x110, v2
	v_subrev_u32_e32 v2, s8, v1
	v_lshlrev_b32_e32 v196, 2, v3
	s_movk_i32 s2, 0x88
	v_ashrrev_i32_e32 v3, 31, v2
	v_mul_lo_u32 v21, v182, s97
	v_mul_lo_u32 v22, v10, s2
	v_mul_lo_u32 v23, v8, s2
	v_mul_lo_u32 v24, v14, s2
	v_mul_lo_u32 v25, v12, s2
	v_lshlrev_b64 v[2:3], 10, v[2:3]
	v_mov_b32_e32 v14, v0
	v_mov_b32_e32 v15, v0
	s_movk_i32 s2, 0x4400
	s_lshr_b32 s22, s9, 6
	v_lshl_add_u64 v[200:201], s[14:15], 0, v[2:3]
	v_mov_b32_e32 v1, v0
	v_mov_b32_e32 v2, v0
	v_mov_b32_e32 v3, v0
	v_mov_b32_e32 v4, v0
	v_mov_b32_e32 v5, v0
	v_mov_b32_e32 v6, v0
	v_mov_b32_e32 v7, v0
	v_mov_b32_e32 v8, v0
	v_mov_b32_e32 v9, v0
	v_mov_b32_e32 v10, v0
	v_mov_b32_e32 v11, v0
	v_mov_b32_e32 v12, v0
	v_mov_b32_e32 v13, v0
	v_add_u32_e32 v207, v16, v21
	v_add3_u32 v222, v18, v22, s2
	v_add3_u32 v223, v18, v23, s2
	v_add3_u32 v224, v18, v24, s2
	v_add3_u32 v225, v18, v25, s2
	v_add_u32_e32 v226, v17, v26
	v_add_u32_e32 v227, v17, v28
	v_add_u32_e32 v228, v19, v20
	v_add_u32_e32 v229, v19, v27
	v_mov_b64_e32 v[30:31], v[14:15]
	v_mov_b64_e32 v[46:47], v[14:15]
	v_mov_b64_e32 v[62:63], v[14:15]
	v_mov_b64_e32 v[78:79], v[14:15]
	s_add_i32 s23, s22, 2
	v_or_b32_e32 v198, 32, v196
	v_sub_u32_e32 v205, v197, v196
	v_mov_b32_e32 v206, 0
	v_mov_b32_e32 v230, 0xff800000
	s_mov_b32 s84, 64
	s_mov_b32 s24, -2
	v_mov_b64_e32 v[28:29], v[12:13]
	v_mov_b64_e32 v[26:27], v[10:11]
	v_mov_b64_e32 v[24:25], v[8:9]
	v_mov_b64_e32 v[22:23], v[6:7]
	v_mov_b64_e32 v[20:21], v[4:5]
	v_mov_b64_e32 v[18:19], v[2:3]
	v_mov_b64_e32 v[16:17], v[0:1]
	v_mov_b64_e32 v[44:45], v[12:13]
	v_mov_b64_e32 v[42:43], v[10:11]
	v_mov_b64_e32 v[40:41], v[8:9]
	v_mov_b64_e32 v[38:39], v[6:7]
	v_mov_b64_e32 v[36:37], v[4:5]
	v_mov_b64_e32 v[34:35], v[2:3]
	v_mov_b64_e32 v[32:33], v[0:1]
	v_mov_b64_e32 v[60:61], v[12:13]
	v_mov_b64_e32 v[58:59], v[10:11]
	v_mov_b64_e32 v[56:57], v[8:9]
	v_mov_b64_e32 v[54:55], v[6:7]
	v_mov_b64_e32 v[52:53], v[4:5]
	v_mov_b64_e32 v[50:51], v[2:3]
	v_mov_b64_e32 v[48:49], v[0:1]
	v_mov_b64_e32 v[76:77], v[12:13]
	v_mov_b64_e32 v[74:75], v[10:11]
	v_mov_b64_e32 v[72:73], v[8:9]
	v_mov_b64_e32 v[70:71], v[6:7]
	v_mov_b64_e32 v[68:69], v[4:5]
	v_mov_b64_e32 v[66:67], v[2:3]
	v_mov_b64_e32 v[64:65], v[0:1]
	s_waitcnt vmcnt(2)
	v_mov_b64_e32 v[2:3], v[202:203]
	s_mov_b32 m0, 0x8c00
	s_mov_b32 s101, 0
	ds_write_b128 v207, v[156:159]
	s_waitcnt vmcnt(1)
	ds_write_b128 v207, v[160:163] offset:4352
	ds_write_b128 v207, v[144:147] offset:8704
	ds_write_b128 v207, v[148:151] offset:13056
	ds_write2_b64 v222, v[152:153], v[154:155] offset1:1
	ds_write2_b64 v223, v[164:165], v[166:167] offset1:1
	ds_write2_b64 v224, v[168:169], v[170:171] offset1:1
	s_waitcnt vmcnt(0)
	ds_write2_b64 v225, v[172:173], v[174:175] offset1:1
	v_add_u32_e32 v207, m0, v207
	v_add_u32_e32 v222, m0, v222
	v_add_u32_e32 v223, m0, v223
	v_add_u32_e32 v224, m0, v224
	v_add_u32_e32 v225, m0, v225
	s_cmp_lt_u32 s23, 2
	s_cbranch_scc1 .Ldsa_pro_done
	s_mov_b32 s100, s84
	v_add_u32_e32 v2, s100, v182
	v_ashrrev_i32_e32 v3, 31, v2
	v_add_u32_e32 v6, 16, v2
	v_lshlrev_b64 v[4:5], 8, v[2:3]
	v_ashrrev_i32_e32 v7, 31, v6
	v_lshl_add_u64 v[4:5], v[184:185], 0, v[4:5]
	v_lshlrev_b64 v[6:7], 8, v[6:7]
	v_lshl_add_u64 v[6:7], v[184:185], 0, v[6:7]
	global_load_dwordx4 v[156:159], v[4:5], off
	global_load_dwordx4 v[160:163], v[6:7], off
	v_add_u32_e32 v4, 32, v2
	v_add_u32_e32 v2, 48, v2
	v_ashrrev_i32_e32 v5, 31, v4
	v_ashrrev_i32_e32 v3, 31, v2
	v_lshlrev_b64 v[4:5], 8, v[4:5]
	v_lshlrev_b64 v[2:3], 8, v[2:3]
	v_lshl_add_u64 v[4:5], v[184:185], 0, v[4:5]
	v_lshl_add_u64 v[2:3], v[184:185], 0, v[2:3]
	global_load_dwordx4 v[144:147], v[4:5], off
	global_load_dwordx4 v[148:151], v[2:3], off
	v_lshl_add_u64 v[2:3], s[100:101], 1, v[186:187]
	v_lshl_add_u64 v[4:5], v[2:3], 0, v[188:189]
	v_lshl_add_u64 v[6:7], v[2:3], 0, v[190:191]
	global_load_dwordx4 v[152:155], v[4:5], off
	global_load_dwordx4 v[164:167], v[6:7], off
	v_lshl_add_u64 v[4:5], v[2:3], 0, v[192:193]
	v_lshl_add_u64 v[2:3], v[2:3], 0, v[194:195]
	global_load_dwordx4 v[168:171], v[4:5], off
	global_load_dwordx4 v[172:175], v[2:3], off
.Ldsa_pro_done:
.LBB0_760:
	s_waitcnt lgkmcnt(0)
	s_barrier
	s_add_i32 s2, s24, 3
	s_cmp_ge_u32 s2, s23
	s_cbranch_scc1 .LBB0_762
	s_waitcnt vmcnt(0)
	ds_write_b128 v207, v[156:159]
	ds_write_b128 v207, v[160:163] offset:4352
	ds_write_b128 v207, v[144:147] offset:8704
	ds_write_b128 v207, v[148:151] offset:13056
	ds_write2_b64 v222, v[152:153], v[154:155] offset1:1
	ds_write2_b64 v223, v[164:165], v[166:167] offset1:1
	ds_write2_b64 v224, v[168:169], v[170:171] offset1:1
	ds_write2_b64 v225, v[172:173], v[174:175] offset1:1
	s_add_i32 s2, s24, 4
	s_cmp_ge_u32 s2, s23
	s_cbranch_scc1 .Ldsa_nopf2
	s_add_i32 s100, s84, 64
	v_add_u32_e32 v2, s100, v182
	v_ashrrev_i32_e32 v3, 31, v2
	v_add_u32_e32 v6, 16, v2
	v_lshlrev_b64 v[4:5], 8, v[2:3]
	v_ashrrev_i32_e32 v7, 31, v6
	v_lshl_add_u64 v[4:5], v[184:185], 0, v[4:5]
	v_lshlrev_b64 v[6:7], 8, v[6:7]
	v_lshl_add_u64 v[6:7], v[184:185], 0, v[6:7]
	global_load_dwordx4 v[156:159], v[4:5], off
	global_load_dwordx4 v[160:163], v[6:7], off
	v_add_u32_e32 v4, 32, v2
	v_add_u32_e32 v2, 48, v2
	v_ashrrev_i32_e32 v5, 31, v4
	v_ashrrev_i32_e32 v3, 31, v2
	v_lshlrev_b64 v[4:5], 8, v[4:5]
	v_lshlrev_b64 v[2:3], 8, v[2:3]
	v_lshl_add_u64 v[4:5], v[184:185], 0, v[4:5]
	v_lshl_add_u64 v[2:3], v[184:185], 0, v[2:3]
	global_load_dwordx4 v[144:147], v[4:5], off
	global_load_dwordx4 v[148:151], v[2:3], off
	v_lshl_add_u64 v[2:3], s[100:101], 1, v[186:187]
	v_lshl_add_u64 v[4:5], v[2:3], 0, v[188:189]
	v_lshl_add_u64 v[6:7], v[2:3], 0, v[190:191]
	global_load_dwordx4 v[152:155], v[4:5], off
	global_load_dwordx4 v[164:167], v[6:7], off
	v_lshl_add_u64 v[4:5], v[2:3], 0, v[192:193]
	v_lshl_add_u64 v[2:3], v[2:3], 0, v[194:195]
	global_load_dwordx4 v[168:171], v[4:5], off
	global_load_dwordx4 v[172:175], v[2:3], off
.Ldsa_nopf2:
	global_load_dwordx2 v[2:3], v[200:201], off

.LBB0_779:
	v_max_i32_e32 v96, 27, v1
	v_subrev_u32_e32 v96, 27, v96
	v_min_u32_e32 v96, 0x80, v96
	v_lshlrev_b32_e32 v96, 2, v96
	ds_read_b32 v111, v96 offset:34816

.LBB0_789:
	v_exp_f32_e32 v11, v6
	s_setprio 1
	v_add_u32_e32 v7, 0x4000, v228
	ds_read2_b64 v[12:15], v7 offset0:128 offset1:130
	v_cvt_pk_bf16_f32 v80, v80, v81
	v_cvt_pk_bf16_f32 v81, v82, v83
	v_cvt_pk_bf16_f32 v82, v84, v85
	v_cvt_pk_bf16_f32 v83, v86, v87
	v_add_u32_e32 v8, 0x4000, v229
	v_add_u32_e32 v9, 0x6000, v228
	v_add_u32_e32 v10, 0x7000, v228
	s_waitcnt lgkmcnt(0)
	v_mfma_f32_32x32x16_bf16 v[64:79], v[12:15], v[80:83], v[64:79]
	ds_read2_b64 v[12:15], v8 offset0:128 offset1:130
	s_waitcnt lgkmcnt(0)
	v_mfma_f32_32x32x16_bf16 v[48:63], v[12:15], v[80:83], v[48:63]
	ds_read2_b64 v[12:15], v9 offset0:192 offset1:194
	s_waitcnt lgkmcnt(0)
	v_mfma_f32_32x32x16_bf16 v[32:47], v[12:15], v[80:83], v[32:47]
	ds_read2_b64 v[12:15], v10 offset0:224 offset1:226
	s_waitcnt lgkmcnt(0)
	v_mfma_f32_32x32x16_bf16 v[16:31], v[12:15], v[80:83], v[16:31]
	ds_read2_b64 v[12:15], v7 offset0:132 offset1:134
	v_cvt_pk_bf16_f32 v80, v88, v89
	v_cvt_pk_bf16_f32 v81, v90, v91
	v_cvt_pk_bf16_f32 v82, v92, v93
	v_cvt_pk_bf16_f32 v83, v94, v11
	s_waitcnt lgkmcnt(0)
	s_nop 0
	v_mfma_f32_32x32x16_bf16 v[64:79], v[12:15], v[80:83], v[64:79]
	ds_read2_b64 v[12:15], v8 offset0:132 offset1:134
	s_waitcnt lgkmcnt(0)
	v_mfma_f32_32x32x16_bf16 v[48:63], v[12:15], v[80:83], v[48:63]
	ds_read2_b64 v[12:15], v9 offset0:196 offset1:198
	s_waitcnt lgkmcnt(0)
	v_mfma_f32_32x32x16_bf16 v[32:47], v[12:15], v[80:83], v[32:47]
	ds_read2_b64 v[12:15], v10 offset0:228 offset1:230
	s_waitcnt lgkmcnt(0)
	v_mfma_f32_32x32x16_bf16 v[16:31], v[12:15], v[80:83], v[16:31]
	s_setprio 0
	s_setprio 1
	ds_read_b128 v[12:15], v227
	s_waitcnt lgkmcnt(0)
	v_mfma_f32_32x32x16_bf16 v[96:111], v[12:15], v[112:115], 0
	ds_read_b128 v[12:15], v227 offset:32
	s_waitcnt lgkmcnt(0)
	v_mfma_f32_32x32x16_bf16 v[96:111], v[12:15], v[116:119], v[96:111]
	ds_read_b128 v[12:15], v227 offset:64
	s_waitcnt lgkmcnt(0)
	v_mfma_f32_32x32x16_bf16 v[96:111], v[12:15], v[120:123], v[96:111]
	ds_read_b128 v[12:15], v227 offset:96
	s_waitcnt lgkmcnt(0)
	v_mfma_f32_32x32x16_bf16 v[96:111], v[12:15], v[124:127], v[96:111]
	ds_read_b128 v[12:15], v227 offset:128
	s_waitcnt lgkmcnt(0)
	v_mfma_f32_32x32x16_bf16 v[96:111], v[12:15], v[128:131], v[96:111]
	ds_read_b128 v[12:15], v227 offset:160
	s_waitcnt lgkmcnt(0)
	v_mfma_f32_32x32x16_bf16 v[96:111], v[12:15], v[132:135], v[96:111]
	ds_read_b128 v[12:15], v227 offset:192
	s_waitcnt lgkmcnt(0)
	v_mfma_f32_32x32x16_bf16 v[96:111], v[12:15], v[136:139], v[96:111]
	ds_read_b128 v[12:15], v227 offset:224
	s_waitcnt lgkmcnt(0)
	v_mfma_f32_32x32x16_bf16 v[96:111], v[12:15], v[140:143], v[96:111]
	s_setprio 0
	v_lshrrev_b64 v[80:81], v198, v[202:203]
	v_and_b32_e32 v238, 1, v80
	v_and_b32_e32 v237, 2, v80
	v_and_b32_e32 v236, 4, v80
	v_and_b32_e32 v235, 8, v80
	v_and_b32_e32 v234, 0x100, v80
	v_and_b32_e32 v233, 0x200, v80
	v_and_b32_e32 v232, 0x400, v80
	v_and_b32_e32 v231, 0x800, v80
	v_and_b32_e32 v230, 0x10000, v80
	v_and_b32_e32 v203, 0x20000, v80
	v_and_b32_e32 v202, 0x40000, v80
	v_and_b32_e32 v15, 0x80000, v80
	v_and_b32_e32 v14, 0x1000000, v80
	v_and_b32_e32 v13, 0x2000000, v80
	v_and_b32_e32 v12, 0x4000000, v80
	v_and_b32_e32 v6, 0x8000000, v80
	s_and_saveexec_b64 s[2:3], vcc
	s_xor_b64 s[2:3], exec, s[2:3]
	s_cbranch_execz .LBB0_791
	v_add3_u32 v95, v205, v183, 31
	v_cmp_eq_u32_e64 s[6:7], 1, v238
	v_max_i32_e32 v81, 1, v95
	v_max_i32_e32 v82, 2, v95
	v_max_i32_e32 v83, 3, v95
	v_max_i32_e32 v84, 8, v95
	v_max_i32_e32 v85, 9, v95
	v_max_i32_e32 v86, 10, v95
	v_max_i32_e32 v87, 11, v95
	v_add_u32_e32 v81, -1, v81
	v_add_u32_e32 v82, -2, v82
	v_add_u32_e32 v83, -3, v83
	v_add_u32_e32 v84, -8, v84
	v_add_u32_e32 v85, -9, v85
	v_add_u32_e32 v86, -10, v86
	v_add_u32_e32 v87, -11, v87
	v_med3_i32 v80, v95, 0, v219
	v_min_u32_e32 v81, 0x80, v81
	v_min_u32_e32 v82, 0x80, v82
	v_min_u32_e32 v83, 0x80, v83
	v_min_u32_e32 v84, 0x80, v84
	v_min_u32_e32 v85, 0x80, v85
	v_min_u32_e32 v86, 0x80, v86
	v_min_u32_e32 v87, 0x80, v87
	v_lshlrev_b32_e32 v80, 2, v80
	v_lshlrev_b32_e32 v81, 2, v81
	v_lshlrev_b32_e32 v82, 2, v82
	v_lshlrev_b32_e32 v83, 2, v83
	v_lshlrev_b32_e32 v84, 2, v84
	v_lshlrev_b32_e32 v85, 2, v85
	v_lshlrev_b32_e32 v86, 2, v86
	v_lshlrev_b32_e32 v87, 2, v87
	v_cmp_lt_i32_e64 s[4:5], -1, v95
	ds_read_b32 v80, v80 offset:34816
	ds_read_b32 v81, v81 offset:34816
	ds_read_b32 v82, v82 offset:34816
	ds_read_b32 v83, v83 offset:34816
	ds_read_b32 v84, v84 offset:34816
	ds_read_b32 v85, v85 offset:34816
	ds_read_b32 v86, v86 offset:34816
	ds_read_b32 v87, v87 offset:34816
	s_waitcnt lgkmcnt(7)
	v_fmac_f32_e32 v80, 0x3e0293ee, v96
	s_and_b64 s[4:5], s[4:5], s[6:7]
	v_cndmask_b32_e64 v80, v221, v80, s[4:5]
	v_cmp_lt_i32_e64 s[4:5], 0, v95
	v_cmp_ne_u32_e64 s[6:7], 0, v237
	s_waitcnt lgkmcnt(6)
	v_fmac_f32_e32 v81, 0x3e0293ee, v97
	s_and_b64 s[4:5], s[4:5], s[6:7]
	v_cndmask_b32_e64 v81, v221, v81, s[4:5]
	v_cmp_lt_i32_e64 s[4:5], 1, v95
	v_cmp_ne_u32_e64 s[6:7], 0, v236
	s_waitcnt lgkmcnt(5)
	v_fmac_f32_e32 v82, 0x3e0293ee, v98
	s_and_b64 s[4:5], s[4:5], s[6:7]
	v_cndmask_b32_e64 v82, v221, v82, s[4:5]
	v_cmp_lt_i32_e64 s[4:5], 2, v95
	v_cmp_ne_u32_e64 s[6:7], 0, v235
	s_waitcnt lgkmcnt(4)
	v_fmac_f32_e32 v83, 0x3e0293ee, v99
	s_and_b64 s[4:5], s[4:5], s[6:7]
	v_cndmask_b32_e64 v83, v221, v83, s[4:5]
	v_cmp_lt_i32_e64 s[4:5], 7, v95
	v_cmp_ne_u32_e64 s[6:7], 0, v234
	s_waitcnt lgkmcnt(3)
	v_fmac_f32_e32 v84, 0x3e0293ee, v100
	s_and_b64 s[4:5], s[4:5], s[6:7]
	v_cndmask_b32_e64 v84, v221, v84, s[4:5]
	v_cmp_lt_i32_e64 s[4:5], 8, v95
	v_cmp_ne_u32_e64 s[6:7], 0, v233
	s_waitcnt lgkmcnt(2)
	v_fmac_f32_e32 v85, 0x3e0293ee, v101
	s_and_b64 s[4:5], s[4:5], s[6:7]
	v_cndmask_b32_e64 v85, v221, v85, s[4:5]
	v_cmp_lt_i32_e64 s[4:5], 9, v95
	v_cmp_ne_u32_e64 s[6:7], 0, v232
	s_waitcnt lgkmcnt(1)
	v_fmac_f32_e32 v86, 0x3e0293ee, v102
	s_and_b64 s[4:5], s[4:5], s[6:7]
	v_max3_f32 v88, v80, s64, v81
	v_cndmask_b32_e64 v86, v221, v86, s[4:5]
	v_cmp_lt_i32_e64 s[4:5], 10, v95
	v_cmp_ne_u32_e64 s[6:7], 0, v231
	v_max3_f32 v88, v88, v82, v83
	s_waitcnt lgkmcnt(0)
	v_fmac_f32_e32 v87, 0x3e0293ee, v103
	s_and_b64 s[4:5], s[4:5], s[6:7]
	v_max3_f32 v88, v88, v84, v85
	v_cndmask_b32_e64 v87, v221, v87, s[4:5]
	v_max3_f32 v90, v88, v86, v87
	v_max_i32_e32 v88, 16, v95
	v_max_i32_e32 v89, 17, v95
	v_max_i32_e32 v91, 18, v95
	v_max_i32_e32 v92, 19, v95
	v_max_i32_e32 v93, 24, v95
	v_max_i32_e32 v94, 25, v95
	v_max_i32_e32 v96, 26, v95
	v_max_i32_e32 v97, 27, v95
	v_add_u32_e32 v88, -16, v88
	v_subrev_u32_e32 v89, 17, v89
	v_subrev_u32_e32 v91, 18, v91
	v_subrev_u32_e32 v92, 19, v92
	v_subrev_u32_e32 v93, 24, v93
	v_subrev_u32_e32 v94, 25, v94
	v_subrev_u32_e32 v96, 26, v96
	v_subrev_u32_e32 v97, 27, v97
	v_min_u32_e32 v88, 0x80, v88
	v_min_u32_e32 v89, 0x80, v89
	v_min_u32_e32 v91, 0x80, v91
	v_min_u32_e32 v92, 0x80, v92
	v_min_u32_e32 v93, 0x80, v93
	v_min_u32_e32 v94, 0x80, v94
	v_min_u32_e32 v96, 0x80, v96
	v_min_u32_e32 v97, 0x80, v97
	v_lshlrev_b32_e32 v88, 2, v88
	v_lshlrev_b32_e32 v89, 2, v89
	v_lshlrev_b32_e32 v91, 2, v91
	v_lshlrev_b32_e32 v92, 2, v92
	v_lshlrev_b32_e32 v93, 2, v93
	v_lshlrev_b32_e32 v94, 2, v94
	v_lshlrev_b32_e32 v96, 2, v96
	v_lshlrev_b32_e32 v97, 2, v97
	v_cmp_lt_i32_e64 s[4:5], 15, v95
	v_cmp_ne_u32_e64 s[6:7], 0, v230
	ds_read_b32 v88, v88 offset:34816
	ds_read_b32 v89, v89 offset:34816
	ds_read_b32 v91, v91 offset:34816
	ds_read_b32 v92, v92 offset:34816
	ds_read_b32 v93, v93 offset:34816
	ds_read_b32 v94, v94 offset:34816
	ds_read_b32 v96, v96 offset:34816
	ds_read_b32 v97, v97 offset:34816
	s_waitcnt lgkmcnt(7)
	v_fmac_f32_e32 v88, 0x3e0293ee, v104
	s_and_b64 s[4:5], s[4:5], s[6:7]
	v_cndmask_b32_e64 v88, v221, v88, s[4:5]
	v_cmp_lt_i32_e64 s[4:5], 16, v95
	v_cmp_ne_u32_e64 s[6:7], 0, v203
	s_waitcnt lgkmcnt(6)
	v_fmac_f32_e32 v89, 0x3e0293ee, v105
	s_and_b64 s[4:5], s[4:5], s[6:7]
	v_cndmask_b32_e64 v89, v221, v89, s[4:5]
	v_cmp_lt_i32_e64 s[4:5], 17, v95
	v_cmp_ne_u32_e64 s[6:7], 0, v202
	s_waitcnt lgkmcnt(5)
	v_fmac_f32_e32 v91, 0x3e0293ee, v106
	s_and_b64 s[4:5], s[4:5], s[6:7]
	v_max3_f32 v98, v90, v88, v89
	v_cndmask_b32_e64 v90, v221, v91, s[4:5]
	v_cmp_lt_i32_e64 s[4:5], 18, v95
	v_cmp_ne_u32_e64 s[6:7], 0, v15
	s_waitcnt lgkmcnt(4)
	v_fmac_f32_e32 v92, 0x3e0293ee, v107
	s_and_b64 s[4:5], s[4:5], s[6:7]
	v_cndmask_b32_e64 v91, v221, v92, s[4:5]
	v_cmp_lt_i32_e64 s[4:5], 23, v95
	v_cmp_ne_u32_e64 s[6:7], 0, v14
	s_waitcnt lgkmcnt(3)
	v_fmac_f32_e32 v93, 0x3e0293ee, v108
	s_and_b64 s[4:5], s[4:5], s[6:7]
	v_cndmask_b32_e64 v92, v221, v93, s[4:5]
	v_cmp_lt_i32_e64 s[4:5], 24, v95
	v_cmp_ne_u32_e64 s[6:7], 0, v13
	s_waitcnt lgkmcnt(2)
	v_fmac_f32_e32 v94, 0x3e0293ee, v109
	s_and_b64 s[4:5], s[4:5], s[6:7]
	v_cndmask_b32_e64 v93, v221, v94, s[4:5]
	v_cmp_lt_i32_e64 s[4:5], 25, v95
	v_cmp_ne_u32_e64 s[6:7], 0, v12
	s_waitcnt lgkmcnt(1)
	v_fmac_f32_e32 v96, 0x3e0293ee, v110
	s_and_b64 s[4:5], s[4:5], s[6:7]
	v_cndmask_b32_e64 v94, v221, v96, s[4:5]
	v_cmp_lt_i32_e64 s[4:5], 26, v95
	v_cmp_ne_u32_e64 s[6:7], 0, v6
	v_max3_f32 v15, v98, v90, v91
	s_waitcnt lgkmcnt(0)
	v_fmac_f32_e32 v97, 0x3e0293ee, v111
	s_and_b64 s[4:5], s[4:5], s[6:7]
	v_max3_f32 v13, v15, v92, v93
	v_cndmask_b32_e64 v95, v221, v97, s[4:5]
	v_max3_f32 v239, v13, v94, v95

.LBB0_799:
	v_exp_f32_e32 v84, v12
	v_add_f32_e32 v1, v11, v1
	v_fmac_f32_e32 v1, v206, v4
	v_add_f32_e32 v206, v84, v13
	v_fmac_f32_e32 v206, v1, v6
	s_setprio 1
	ds_read2_b64 v[12:15], v7 offset0:136 offset1:138
	v_cvt_pk_bf16_f32 v80, v96, v97
	v_cvt_pk_bf16_f32 v81, v98, v99
	v_cvt_pk_bf16_f32 v82, v100, v101
	v_cvt_pk_bf16_f32 v83, v102, v103
	ds_read2_b64 v[4:7], v7 offset0:140 offset1:142
	s_waitcnt lgkmcnt(1)
	v_mfma_f32_32x32x16_bf16 v[64:79], v[12:15], v[80:83], v[64:79]
	ds_read2_b64 v[12:15], v8 offset0:136 offset1:138
	s_waitcnt lgkmcnt(0)
	v_mfma_f32_32x32x16_bf16 v[48:63], v[12:15], v[80:83], v[48:63]
	ds_read2_b64 v[12:15], v9 offset0:200 offset1:202
	s_waitcnt lgkmcnt(0)
	v_mfma_f32_32x32x16_bf16 v[32:47], v[12:15], v[80:83], v[32:47]
	ds_read2_b64 v[12:15], v10 offset0:232 offset1:234
	s_waitcnt lgkmcnt(0)
	v_mfma_f32_32x32x16_bf16 v[16:31], v[12:15], v[80:83], v[16:31]
	v_cvt_pk_bf16_f32 v12, v104, v105
	v_cvt_pk_bf16_f32 v13, v106, v107
	v_cvt_pk_bf16_f32 v14, v108, v109
	v_cvt_pk_bf16_f32 v15, v110, v84
	s_nop 1
	v_mfma_f32_32x32x16_bf16 v[64:79], v[4:7], v[12:15], v[64:79]
	ds_read2_b64 v[4:7], v8 offset0:140 offset1:142
	s_waitcnt lgkmcnt(0)
	v_mfma_f32_32x32x16_bf16 v[48:63], v[4:7], v[12:15], v[48:63]
	ds_read2_b64 v[4:7], v9 offset0:204 offset1:206
	s_waitcnt lgkmcnt(0)
	v_mfma_f32_32x32x16_bf16 v[32:47], v[4:7], v[12:15], v[32:47]
	ds_read2_b64 v[4:7], v10 offset0:236 offset1:238
	s_waitcnt lgkmcnt(0)
	v_mfma_f32_32x32x16_bf16 v[16:31], v[4:7], v[12:15], v[16:31]
	s_setprio 0
	v_add_u32_e32 v226, m0, v226
	v_add_u32_e32 v227, m0, v227
	v_add_u32_e32 v228, m0, v228
	v_add_u32_e32 v229, m0, v229
	v_subrev_u32_e32 v207, m0, v207
	v_subrev_u32_e32 v222, m0, v222
	v_subrev_u32_e32 v223, m0, v223
	v_subrev_u32_e32 v224, m0, v224
	v_subrev_u32_e32 v225, m0, v225
	s_sub_i32 m0, 0, m0
	s_add_i32 s84, s84, 64
	s_add_i32 s24, s24, 1
	v_lshl_add_u64 v[200:201], v[200:201], 0, 8
	s_cmp_lg_u32 s22, s24
	v_subrev_u32_e32 v183, 64, v183
	s_cbranch_scc0 .LBB0_750
	s_waitcnt vmcnt(0)
	v_mov_b64_e32 v[202:203], v[2:3]
	s_branch .LBB0_760
.LBB0_801:
	v_med3_i32 v5, v1, 0, v219
	v_lshlrev_b32_e32 v5, 2, v5
	ds_read_b32 v5, v5 offset:34816
	s_or_b64 exec, exec, s[6:7]
	v_mov_b32_e32 v6, v179
	s_and_saveexec_b64 s[6:7], vcc
	s_cbranch_execz .LBB0_765
.LBB0_802:
	v_max_i32_e32 v6, 1, v1
	v_add_u32_e32 v6, -1, v6
	v_min_u32_e32 v6, 0x80, v6
	v_lshlrev_b32_e32 v6, 2, v6
	ds_read_b32 v6, v6 offset:34816
	s_or_b64 exec, exec, s[6:7]
	v_mov_b32_e32 v7, v179
	s_and_saveexec_b64 s[6:7], vcc
	s_cbranch_execz .LBB0_766
.LBB0_803:
	v_max_i32_e32 v7, 2, v1
	v_add_u32_e32 v7, -2, v7
	v_min_u32_e32 v7, 0x80, v7
	v_lshlrev_b32_e32 v7, 2, v7
	ds_read_b32 v7, v7 offset:34816
	s_or_b64 exec, exec, s[6:7]
	v_mov_b32_e32 v8, v179
	s_and_saveexec_b64 s[6:7], vcc
	s_cbranch_execz .LBB0_767
.LBB0_804:
	v_max_i32_e32 v8, 3, v1
	v_add_u32_e32 v8, -3, v8
	v_min_u32_e32 v8, 0x80, v8
	v_lshlrev_b32_e32 v8, 2, v8
	ds_read_b32 v8, v8 offset:34816
	s_or_b64 exec, exec, s[6:7]
	v_mov_b32_e32 v9, v179
	s_and_saveexec_b64 s[6:7], vcc
	s_cbranch_execz .LBB0_768
.LBB0_805:
	v_max_i32_e32 v9, 8, v1
	v_add_u32_e32 v9, -8, v9
	v_min_u32_e32 v9, 0x80, v9
	v_lshlrev_b32_e32 v9, 2, v9
	ds_read_b32 v9, v9 offset:34816
	s_or_b64 exec, exec, s[6:7]
	v_mov_b32_e32 v10, v179
	s_and_saveexec_b64 s[6:7], vcc
	s_cbranch_execz .LBB0_769
.LBB0_806:
	v_max_i32_e32 v10, 9, v1
	v_add_u32_e32 v10, -9, v10
	v_min_u32_e32 v10, 0x80, v10
	v_lshlrev_b32_e32 v10, 2, v10
	ds_read_b32 v10, v10 offset:34816
	s_or_b64 exec, exec, s[6:7]
	v_mov_b32_e32 v11, v179
	s_and_saveexec_b64 s[6:7], vcc
	s_cbranch_execz .LBB0_770
.LBB0_807:
	v_max_i32_e32 v11, 10, v1
	v_add_u32_e32 v11, -10, v11
	v_min_u32_e32 v11, 0x80, v11
	v_lshlrev_b32_e32 v11, 2, v11
	ds_read_b32 v11, v11 offset:34816
	s_or_b64 exec, exec, s[6:7]
	v_mov_b32_e32 v12, v179
	s_and_saveexec_b64 s[6:7], vcc
	s_cbranch_execz .LBB0_771
.LBB0_808:
	v_max_i32_e32 v12, 11, v1
	v_add_u32_e32 v12, -11, v12
	v_min_u32_e32 v12, 0x80, v12
	v_lshlrev_b32_e32 v12, 2, v12
	ds_read_b32 v12, v12 offset:34816
	s_or_b64 exec, exec, s[6:7]
	v_mov_b32_e32 v13, v179
	s_and_saveexec_b64 s[6:7], vcc
	s_cbranch_execz .LBB0_772
.LBB0_809:
	v_max_i32_e32 v13, 16, v1
	v_add_u32_e32 v13, -16, v13
	v_min_u32_e32 v13, 0x80, v13
	v_lshlrev_b32_e32 v13, 2, v13
	ds_read_b32 v13, v13 offset:34816
	s_or_b64 exec, exec, s[6:7]
	v_mov_b32_e32 v14, v179
	s_and_saveexec_b64 s[6:7], vcc
	s_cbranch_execz .LBB0_773
.LBB0_810:
	v_max_i32_e32 v14, 17, v1
	v_subrev_u32_e32 v14, 17, v14
	v_min_u32_e32 v14, 0x80, v14
	v_lshlrev_b32_e32 v14, 2, v14
	ds_read_b32 v14, v14 offset:34816
	s_or_b64 exec, exec, s[6:7]
	v_mov_b32_e32 v15, v179
	s_and_saveexec_b64 s[6:7], vcc
	s_cbranch_execz .LBB0_774
.LBB0_811:
	v_max_i32_e32 v15, 18, v1
	v_subrev_u32_e32 v15, 18, v15
	v_min_u32_e32 v15, 0x80, v15
	v_lshlrev_b32_e32 v15, 2, v15
	ds_read_b32 v15, v15 offset:34816
	s_or_b64 exec, exec, s[6:7]
	v_mov_b32_e32 v107, v179
	s_and_saveexec_b64 s[6:7], vcc
	s_cbranch_execz .LBB0_775
.LBB0_812:
	v_max_i32_e32 v96, 19, v1
	v_subrev_u32_e32 v96, 19, v96
	v_min_u32_e32 v96, 0x80, v96
	v_lshlrev_b32_e32 v96, 2, v96
	ds_read_b32 v107, v96 offset:34816
	s_or_b64 exec, exec, s[6:7]
	v_mov_b32_e32 v108, v179
	s_and_saveexec_b64 s[6:7], vcc
	s_cbranch_execz .LBB0_776
.LBB0_813:
	v_max_i32_e32 v96, 24, v1
	v_subrev_u32_e32 v96, 24, v96
	v_min_u32_e32 v96, 0x80, v96
	v_lshlrev_b32_e32 v96, 2, v96
	ds_read_b32 v108, v96 offset:34816
	s_or_b64 exec, exec, s[6:7]
	v_mov_b32_e32 v109, v179
	s_and_saveexec_b64 s[6:7], vcc
	s_cbranch_execz .LBB0_777
.LBB0_814:
	v_max_i32_e32 v96, 25, v1
	v_subrev_u32_e32 v96, 25, v96
	v_min_u32_e32 v96, 0x80, v96
	v_lshlrev_b32_e32 v96, 2, v96
	ds_read_b32 v109, v96 offset:34816
	s_or_b64 exec, exec, s[6:7]
	v_mov_b32_e32 v110, v179
	s_and_saveexec_b64 s[6:7], vcc
	s_cbranch_execz .LBB0_778
.LBB0_815:
	v_max_i32_e32 v96, 26, v1
	v_subrev_u32_e32 v96, 26, v96
	v_min_u32_e32 v96, 0x80, v96
	v_lshlrev_b32_e32 v96, 2, v96
	ds_read_b32 v110, v96 offset:34816
	s_or_b64 exec, exec, s[6:7]
	v_mov_b32_e32 v111, v179
	s_and_saveexec_b64 s[6:7], vcc
	s_cbranch_execnz .LBB0_779
	s_branch .LBB0_780

.LBB0_1642:
	s_waitcnt vmcnt(0)
	v_mov_b32_e32 v1, v208
	s_barrier
	s_nop 0
	v_cmp_eq_u32_e32 vcc, 0, v1
	s_and_saveexec_b64 s[0:1], vcc
	v_readlane_b32 s86, v255, 12
	v_readlane_b32 s87, v255, 13
	v_readlane_b32 s76, v255, 15
	v_readlane_b32 s94, v254, 11
	v_readlane_b32 s77, v255, 16
	s_mov_b32 s87, 0x1ffffc0
	v_readlane_b32 s95, v254, 12
	s_cbranch_execz .LBB0_1694
	v_mov_b32_e32 v1, 0x12100
	s_getreg_b32 s2, hwreg(HW_REG_XCC_ID, 0, 4)
	s_waitcnt vmcnt(0) expcnt(0) lgkmcnt(0)
	ds_read_b32 v3, v1
	v_mov_b32_e32 v1, 0x12104
	ds_read_b32 v2, v1
	s_and_b32 s8, s2, 15
	s_waitcnt lgkmcnt(1)
	v_cmp_ne_u32_e32 vcc, 0, v3
	s_cbranch_vccnz .LBB0_1658
	s_mov_b32 s9, 1
	s_branch .LBB0_1646

.LBB0_1973:
	s_waitcnt vmcnt(0)
	v_mov_b32_e32 v1, v208
	s_barrier
	s_nop 0
	v_cmp_eq_u32_e32 vcc, 0, v1
	s_and_saveexec_b64 s[0:1], vcc
	s_cbranch_execz .LBB0_2025
	v_mov_b32_e32 v1, 0x12100
	s_getreg_b32 s4, hwreg(HW_REG_XCC_ID, 0, 4)
	s_waitcnt vmcnt(0) expcnt(0) lgkmcnt(0)
	ds_read_b32 v3, v1
	v_mov_b32_e32 v1, 0x12104
	ds_read_b32 v2, v1
	s_and_b32 s10, s4, 15
	s_waitcnt lgkmcnt(1)
	v_cmp_ne_u32_e32 vcc, 0, v3
	s_cbranch_vccnz .LBB0_1989
	s_mov_b32 s11, 1
	s_branch .LBB0_1977

.LBB0_2028:
	s_or_b64 exec, exec, s[6:7]
	s_waitcnt vmcnt(0)
	v_mov_b32_e32 v1, v208
	s_barrier
	s_nop 0
	v_cmp_eq_u32_e32 vcc, 0, v1
	s_and_saveexec_b64 s[4:5], vcc
	s_cbranch_execz .LBB0_2080
	v_mov_b32_e32 v1, 0x12100
	s_getreg_b32 s6, hwreg(HW_REG_XCC_ID, 0, 4)
	s_waitcnt vmcnt(0) expcnt(0) lgkmcnt(0)
	ds_read_b32 v3, v1
	v_mov_b32_e32 v1, 0x12104
	ds_read_b32 v2, v1
	s_and_b32 s12, s6, 15
	s_waitcnt lgkmcnt(1)
	v_cmp_ne_u32_e32 vcc, 0, v3
	s_cbranch_vccnz .LBB0_2044
	s_mov_b32 s13, 1
	s_branch .LBB0_2032

.LBB0_2043:
	s_cmp_eq_u32 s12, 0
	s_cselect_b64 vcc, -1, 0
	s_cmp_eq_u32 s12, 1
	v_cndmask_b32_e32 v17, 0, v1, vcc
	s_cselect_b64 vcc, -1, 0
	s_cmp_eq_u32 s12, 2
	v_cndmask_b32_e32 v17, v17, v2, vcc
	s_cselect_b64 vcc, -1, 0
	s_cmp_eq_u32 s12, 3
	v_cndmask_b32_e32 v17, v17, v3, vcc
	s_cselect_b64 vcc, -1, 0
	s_cmp_eq_u32 s12, 4
	v_cndmask_b32_e32 v17, v17, v4, vcc
	s_cselect_b64 vcc, -1, 0
	s_cmp_eq_u32 s12, 5
	v_cndmask_b32_e32 v17, v17, v5, vcc
	s_cselect_b64 vcc, -1, 0
	s_cmp_eq_u32 s12, 6
	v_cndmask_b32_e32 v17, v17, v6, vcc
	s_cselect_b64 vcc, -1, 0
	s_cmp_eq_u32 s12, 7
	v_cndmask_b32_e32 v17, v17, v7, vcc
	s_cselect_b64 vcc, -1, 0
	s_cmp_eq_u32 s12, 8
	v_cndmask_b32_e32 v17, v17, v8, vcc
	s_cselect_b64 vcc, -1, 0
	s_cmp_eq_u32 s12, 9
	v_cndmask_b32_e32 v17, v17, v9, vcc
	s_cselect_b64 vcc, -1, 0
	s_cmp_eq_u32 s12, 10
	v_cndmask_b32_e32 v17, v17, v10, vcc
	s_cselect_b64 vcc, -1, 0
	s_cmp_eq_u32 s12, 11
	v_cndmask_b32_e32 v17, v17, v11, vcc
	s_cselect_b64 vcc, -1, 0
	s_cmp_eq_u32 s12, 12
	v_cndmask_b32_e32 v17, v17, v12, vcc
	s_cselect_b64 vcc, -1, 0
	s_cmp_eq_u32 s12, 13
	v_cndmask_b32_e32 v17, v17, v13, vcc
	s_cselect_b64 vcc, -1, 0
	s_cmp_eq_u32 s12, 14
	v_cndmask_b32_e32 v17, v17, v14, vcc
	s_cselect_b64 vcc, -1, 0
	s_cmp_eq_u32 s12, 15
	v_cndmask_b32_e32 v17, v17, v15, vcc
	s_cselect_b64 vcc, -1, 0
	v_cndmask_b32_e32 v17, v17, v16, vcc
	v_cmp_ne_u32_e32 vcc, 0, v1
	s_nop 1
	v_cndmask_b32_e64 v1, 0, 1, vcc
	v_cmp_ne_u32_e32 vcc, 0, v2
	s_nop 1
	v_addc_co_u32_e32 v1, vcc, 0, v1, vcc
	v_cmp_ne_u32_e32 vcc, 0, v3
	v_max_u32_e32 v3, 1, v17
	s_nop 0
	v_cndmask_b32_e64 v2, 0, 1, vcc
	v_cmp_ne_u32_e32 vcc, 0, v4
	s_nop 1
	v_addc_co_u32_e32 v1, vcc, v1, v2, vcc
	v_cmp_ne_u32_e32 vcc, 0, v5
	s_nop 1
	v_cndmask_b32_e64 v2, 0, 1, vcc
	v_cmp_ne_u32_e32 vcc, 0, v6
	s_nop 1
	v_addc_co_u32_e32 v1, vcc, v1, v2, vcc
	v_cmp_ne_u32_e32 vcc, 0, v7
	s_nop 1
	v_cndmask_b32_e64 v2, 0, 1, vcc
	v_cmp_ne_u32_e32 vcc, 0, v8
	s_nop 1
	v_addc_co_u32_e32 v1, vcc, v1, v2, vcc
	v_cmp_ne_u32_e32 vcc, 0, v9
	s_nop 1
	v_cndmask_b32_e64 v2, 0, 1, vcc
	v_cmp_ne_u32_e32 vcc, 0, v10
	s_nop 1
	v_addc_co_u32_e32 v1, vcc, v1, v2, vcc
	v_cmp_ne_u32_e32 vcc, 0, v11
	s_nop 1
	v_cndmask_b32_e64 v2, 0, 1, vcc
	v_cmp_ne_u32_e32 vcc, 0, v12
	s_nop 1
	v_addc_co_u32_e32 v1, vcc, v1, v2, vcc
	v_cmp_ne_u32_e32 vcc, 0, v13
	s_nop 1
	v_cndmask_b32_e64 v2, 0, 1, vcc
	v_cmp_ne_u32_e32 vcc, 0, v14
	s_nop 1
	v_addc_co_u32_e32 v1, vcc, v1, v2, vcc
	v_cmp_ne_u32_e32 vcc, 0, v15
	s_nop 1
	v_cndmask_b32_e64 v2, 0, 1, vcc
	v_cmp_ne_u32_e32 vcc, 0, v16
	s_nop 1
	v_addc_co_u32_e32 v1, vcc, v1, v2, vcc
	v_max_u32_e32 v2, 1, v1
	v_mov_b32_e32 v1, 0x12100
	ds_write_b32 v1, v3
	v_mov_b32_e32 v1, 0x12104
	ds_write_b32 v1, v2

.LBB0_2112:
	s_waitcnt vmcnt(0)
	v_mov_b32_e32 v1, v208
	s_barrier
	s_nop 0
	v_cmp_eq_u32_e32 vcc, 0, v1
	s_and_saveexec_b64 s[4:5], vcc
	s_cbranch_execz .LBB0_2164
	v_mov_b32_e32 v1, 0x12100
	s_getreg_b32 s6, hwreg(HW_REG_XCC_ID, 0, 4)
	s_waitcnt vmcnt(0) expcnt(0) lgkmcnt(0)
	ds_read_b32 v3, v1
	v_mov_b32_e32 v1, 0x12104
	ds_read_b32 v2, v1
	s_and_b32 s12, s6, 15
	s_waitcnt lgkmcnt(1)
	v_cmp_ne_u32_e32 vcc, 0, v3
	s_cbranch_vccnz .LBB0_2128
	s_mov_b32 s13, 1
	s_branch .LBB0_2116

.LBB0_2195:
	v_mov_b32_e32 v1, 0x12100
	s_getreg_b32 s2, hwreg(HW_REG_XCC_ID, 0, 4)
	s_waitcnt vmcnt(0) expcnt(0) lgkmcnt(0)
	ds_read_b32 v3, v1
	v_mov_b32_e32 v1, 0x12104
	ds_read_b32 v2, v1
	s_and_b32 s8, s2, 15
	s_waitcnt lgkmcnt(1)
	v_cmp_ne_u32_e32 vcc, 0, v3
	s_cbranch_vccnz .LBB0_2210
	s_mov_b32 s9, 1
	s_branch .LBB0_2198

	.amdhsa_kernel _Z4mega6Params
		.amdhsa_group_segment_fixed_size 74240
		.amdhsa_private_segment_fixed_size 0
		.amdhsa_kernarg_size 496
		.amdhsa_user_sgpr_count 2
		.amdhsa_user_sgpr_dispatch_ptr 0
		.amdhsa_user_sgpr_queue_ptr 0
		.amdhsa_user_sgpr_kernarg_segment_ptr 1
		.amdhsa_user_sgpr_dispatch_id 0
		.amdhsa_user_sgpr_kernarg_preload_length 0
		.amdhsa_user_sgpr_kernarg_preload_offset 0
		.amdhsa_user_sgpr_private_segment_size 0
		.amdhsa_uses_dynamic_stack 0
		.amdhsa_enable_private_segment 0
		.amdhsa_system_sgpr_workgroup_id_x 1
		.amdhsa_system_sgpr_workgroup_id_y 0
		.amdhsa_system_sgpr_workgroup_id_z 0
		.amdhsa_system_sgpr_workgroup_info 0
		.amdhsa_system_vgpr_workitem_id 2
		.amdhsa_next_free_vgpr 256
		.amdhsa_next_free_sgpr 102
		.amdhsa_accum_offset 256
		.amdhsa_reserve_vcc 1
		.amdhsa_float_round_mode_32 0
		.amdhsa_float_round_mode_16_64 0
		.amdhsa_float_denorm_mode_32 3
		.amdhsa_float_denorm_mode_16_64 3
		.amdhsa_dx10_clamp 1
		.amdhsa_ieee_mode 1
		.amdhsa_fp16_overflow 0
		.amdhsa_tg_split 0
		.amdhsa_exception_fp_ieee_invalid_op 0
		.amdhsa_exception_fp_denorm_src 0
		.amdhsa_exception_fp_ieee_div_zero 0
		.amdhsa_exception_fp_ieee_overflow 0
		.amdhsa_exception_fp_ieee_underflow 0
		.amdhsa_exception_fp_ieee_inexact 0
		.amdhsa_exception_int_div_zero 0
	.end_amdhsa_kernel

amdhsa.kernels:
  - .agpr_count:     0
    .args:
      - .offset:         0
        .size:           240
        .value_kind:     by_value
      - .offset:         240
        .size:           4
        .value_kind:     hidden_block_count_x
      - .offset:         244
        .size:           4
        .value_kind:     hidden_block_count_y
      - .offset:         248
        .size:           4
        .value_kind:     hidden_block_count_z
      - .offset:         252
        .size:           2
        .value_kind:     hidden_group_size_x
      - .offset:         254
        .size:           2
        .value_kind:     hidden_group_size_y
      - .offset:         256
        .size:           2
        .value_kind:     hidden_group_size_z
      - .offset:         258
        .size:           2
        .value_kind:     hidden_remainder_x
      - .offset:         260
        .size:           2
        .value_kind:     hidden_remainder_y
      - .offset:         262
        .size:           2
        .value_kind:     hidden_remainder_z
      - .offset:         280
        .size:           8
        .value_kind:     hidden_global_offset_x
      - .offset:         288
        .size:           8
        .value_kind:     hidden_global_offset_y
      - .offset:         296
        .size:           8
        .value_kind:     hidden_global_offset_z
      - .offset:         304
        .size:           2
        .value_kind:     hidden_grid_dims
      - .offset:         328
        .size:           8
        .value_kind:     hidden_multigrid_sync_arg
    .group_segment_fixed_size: 74240
    .kernarg_segment_align: 8
    .kernarg_segment_size: 496
    .language:       OpenCL C
    .language_version:
      - 2
      - 0
    .max_flat_workgroup_size: 256
    .name:           _Z4mega6Params
    .private_segment_fixed_size: 0
    .sgpr_count:     108
    .sgpr_spill_count: 130
    .symbol:         _Z4mega6Params.kd
    .uniform_work_group_size: 1
    .uses_dynamic_stack: false
    .vgpr_count:     256
    .vgpr_spill_count: 0
    .wavefront_size: 64
